# S5 passes: waves 4-7 start 2560 cycles late so the two waves of a SIMD alternate MFMA and VALU phases
# speedup vs baseline: 1.0003x; 1.0003x over previous
; template <bool FINAL>
; __device__ __forceinline__ void s5_wave(const Params& P, int j, int g, int idx0, int stride, char* ldsw) {
;     ...
;   const int p = lane;
;   const int jg = j * 32 + g;
;   const float lr = P.in[I_S5LRE][jg * 64 + p], li = P.in[I_S5LIM][jg * 64 + p];
;   const float dt = expf(P.in[I_S5LOGDT][jg]);
;   const float er = expf(lr * dt);
;   float sn, cs;
;   sincosf(li * dt, &sn, &cs);
;   const float lbr = er * cs, lbi = er * sn;
;   const float nr = lbr - 1.f, ni = lbi;
;   const float den = 1.f / (lr * lr + li * li);
;   const float cr = (nr * lr + ni * li) * den, ci = (ni * lr - nr * li) * den;
;   typedef float f32x2 __attribute__((ext_vector_type(2)));
;   f32x2 bb[16];
;   {
;     const float4* br4 = reinterpret_cast<const float4*>(P.in[I_S5BRE] + ((size_t)jg * 64 + p) * 16);
;     const float4* bi4 = reinterpret_cast<const float4*>(P.in[I_S5BIM] + ((size_t)jg * 64 + p) * 16);
; #pragma unroll
;     for (int q = 0; q < 4; ++q) {
;       float4 a = br4[q], c = bi4[q];
;       bb[4 * q + 0] = (f32x2){cr * a.x - ci * c.x, cr * c.x + ci * a.x};
;       bb[4 * q + 1] = (f32x2){cr * a.y - ci * c.y, cr * c.y + ci * a.y};
;       bb[4 * q + 2] = (f32x2){cr * a.z - ci * c.z, cr * c.z + ci * a.z};
;       bb[4 * q + 3] = (f32x2){cr * a.w - ci * c.w, cr * c.w + ci * a.w};
;     }
;   }
;   const u16* Zo = reinterpret_cast<const u16*>(P.ws + OFF_BIG);
;   float2* hend = reinterpret_cast<float2*>(P.ws + OFF_S5END);
;   uint32_t* hbuf = reinterpret_cast<uint32_t*>(ldsw);
;   float pr = lbr, pi = lbi;
; #pragma unroll
;   for (int s6 = 0; s6 < 6; ++s6) {
;     float nr2 = pr * pr - pi * pi, ni2 = 2.f * pr * pi;
;     pr = nr2; pi = ni2;
;   }
;   const int fr = lane & 15, fq = lane >> 4;
;   bf16x8 bc[4];
;   f32x4 dv4 = {0.f, 0.f, 0.f, 0.f};
;   if (FINAL) {
;     const float* crp = P.in[I_S5CRE] + ((size_t)jg * 16 + fr) * 64;
;     const float* cip = P.in[I_S5CIM] + ((size_t)jg * 16 + fr) * 64;
; #pragma unroll
;     for (int ks = 0; ks < 4; ++ks) {
;       float4 a = *reinterpret_cast<const float4*>(crp + ks * 16 + fq * 4);
;       float4 c = *reinterpret_cast<const float4*>(cip + ks * 16 + fq * 4);
;       union { bf16x8 v; uint32_t w[4]; } uu_;
;       uu_.w[0] = pack2(a.x, -c.x); uu_.w[1] = pack2(a.y, -c.y); uu_.w[2] = pack2(a.z, -c.z); uu_.w[3] = pack2(a.w, -c.w);
;       bc[ks] = uu_.v;
;     }
.LBB0_428:
	s_or_b64 exec, exec, s[0:1]
	v_readlane_b32 s0, v255, 0
	v_readlane_b32 s1, v255, 1
	v_ashrrev_i32_e32 v4, 2, v48
	v_and_b32_e32 v90, 15, v48
	s_lshl_b64 s[0:1], s[0:1], 2
	v_readlane_b32 s4, v250, 50
	v_and_b32_e32 v50, -4, v4
	v_lshl_or_b32 v0, v90, 8, s0
	v_mov_b32_e32 v1, s1
	v_readlane_b32 s12, v250, 58
	v_readlane_b32 s13, v250, 59
	v_ashrrev_i32_e32 v51, 31, v50
	v_readlane_b32 s14, v250, 60
	v_readlane_b32 s15, v250, 61
	v_lshl_add_u64 v[2:3], s[12:13], 0, v[0:1]
	v_lshlrev_b64 v[4:5], 2, v[50:51]
	v_lshl_add_u64 v[0:1], s[14:15], 0, v[0:1]
	v_lshl_add_u64 v[22:23], v[2:3], 0, v[4:5]
	v_lshl_add_u64 v[24:25], v[0:1], 0, v[4:5]
	global_load_dwordx4 v[0:3], v[22:23], off
	global_load_dwordx4 v[4:7], v[24:25], off
	v_readlane_b32 s0, v251, 63
	v_readlane_b32 s1, v252, 0
	s_andn2_b64 vcc, exec, s[0:1]
	v_readlane_b32 s5, v250, 51
	v_readlane_b32 s6, v250, 52
	v_readlane_b32 s7, v250, 53
	v_readlane_b32 s8, v250, 54
	v_readlane_b32 s9, v250, 55
	v_readlane_b32 s10, v250, 56
	v_readlane_b32 s11, v250, 57
	v_readlane_b32 s16, v250, 62
	v_readlane_b32 s17, v250, 63
	v_readlane_b32 s18, v251, 0
	v_readlane_b32 s19, v251, 1
	s_waitcnt vmcnt(0)
	v_xor_b32_e32 v4, 0x80000000, v4
	v_cvt_pk_bf16_f32 v0, v0, v4
	v_xor_b32_e32 v4, 0x80000000, v5
	v_cvt_pk_bf16_f32 v1, v1, v4
	v_xor_b32_e32 v4, 0x80000000, v6
	v_cvt_pk_bf16_f32 v2, v2, v4
	v_xor_b32_e32 v4, 0x80000000, v7
	v_cvt_pk_bf16_f32 v3, v3, v4
	global_load_dwordx4 v[4:7], v[22:23], off offset:64
	global_load_dwordx4 v[8:11], v[24:25], off offset:64
	s_waitcnt vmcnt(0)
	v_xor_b32_e32 v8, 0x80000000, v8
	v_cvt_pk_bf16_f32 v4, v4, v8
	v_xor_b32_e32 v8, 0x80000000, v9
	v_cvt_pk_bf16_f32 v5, v5, v8
	v_xor_b32_e32 v8, 0x80000000, v10
	v_cvt_pk_bf16_f32 v6, v6, v8
	v_xor_b32_e32 v8, 0x80000000, v11
	v_cvt_pk_bf16_f32 v7, v7, v8
	global_load_dwordx4 v[8:11], v[22:23], off offset:128
	global_load_dwordx4 v[12:15], v[24:25], off offset:128
	s_waitcnt vmcnt(0)
	v_xor_b32_e32 v12, 0x80000000, v12
	v_cvt_pk_bf16_f32 v8, v8, v12
	v_xor_b32_e32 v12, 0x80000000, v13
	v_cvt_pk_bf16_f32 v9, v9, v12
	v_xor_b32_e32 v12, 0x80000000, v14
	v_cvt_pk_bf16_f32 v10, v10, v12
	v_xor_b32_e32 v12, 0x80000000, v15
	v_cvt_pk_bf16_f32 v11, v11, v12
	global_load_dwordx4 v[12:15], v[22:23], off offset:192
	s_nop 0
	global_load_dwordx4 v[22:25], v[24:25], off offset:192
	s_waitcnt vmcnt(0)
	v_xor_b32_e32 v21, 0x80000000, v22
	v_cvt_pk_bf16_f32 v12, v12, v21
	v_xor_b32_e32 v21, 0x80000000, v23
	v_cvt_pk_bf16_f32 v13, v13, v21
	v_xor_b32_e32 v21, 0x80000000, v24
	v_cvt_pk_bf16_f32 v14, v14, v21
	v_xor_b32_e32 v21, 0x80000000, v25
	v_cvt_pk_bf16_f32 v15, v15, v21
	s_cbranch_vccnz .LBB0_440
	v_mul_f32_e32 v18, v56, v18
	v_mul_f32_e32 v21, 0x3fb8aa3b, v18
	s_mov_b32 s0, 0x3fb8aa3b
	v_fma_f32 v22, v18, s0, -v21
	v_rndne_f32_e32 v23, v21
	v_fmac_f32_e32 v22, 0x32a5705f, v18
	v_sub_f32_e32 v21, v21, v23
	v_add_f32_e32 v21, v21, v22
	v_exp_f32_e32 v21, v21
	v_cvt_i32_f32_e32 v22, v23
	s_mov_b32 s0, 0xc2ce8ed0
	v_cmp_ngt_f32_e32 vcc, s0, v18
	s_mov_b32 s0, 0x42b17218
	v_ldexp_f32 v21, v21, v22
	v_cndmask_b32_e32 v21, 0, v21, vcc
	v_cmp_nlt_f32_e32 vcc, s0, v18
	v_xor_b32_e32 v17, v17, v16
	s_brev_b32 s0, 1
	v_cndmask_b32_e32 v18, v226, v21, vcc
	v_mul_f32_e32 v21, v19, v19
	v_fmamk_f32 v22, v21, 0xb94c1982, v219
	v_fmaak_f32 v22, v21, v22, 0xbe2aaa9d
	v_mul_f32_e32 v22, v21, v22
	v_fmac_f32_e32 v19, v19, v22
	v_fmamk_f32 v22, v21, 0x37d75334, v220
	v_fmaak_f32 v22, v21, v22, 0x3d2aabf7
	v_fmaak_f32 v22, v21, v22, 0xbf000004
	v_fma_f32 v21, v21, v22, 1.0
	v_lshlrev_b32_e32 v22, 30, v20
	v_and_b32_e32 v20, 1, v20
	v_cmp_eq_u32_e32 vcc, 0, v20
	v_and_b32_e32 v23, 0x80000000, v22
	v_ashrrev_i32_e32 v49, 31, v48
	v_cndmask_b32_e32 v20, v21, v19, vcc
	v_xor_b32_e32 v19, 0x80000000, v19
	v_cndmask_b32_e32 v19, v19, v21, vcc
	v_xor_b32_e32 v17, v17, v20
	v_bitop3_b32 v19, v19, v22, s0 bitop3:0x78
	s_movk_i32 s0, 0x1f8
	v_xor_b32_e32 v17, v17, v23
	v_cmp_class_f32_e64 vcc, v16, s0
	v_readlane_b32 s4, v250, 50
	v_readlane_b32 s8, v250, 54
	v_cndmask_b32_e32 v16, v229, v19, vcc
	v_cndmask_b32_e32 v17, v229, v17, vcc
	v_mul_f32_e32 v52, v18, v16
	v_mul_f32_e32 v55, v18, v17
	v_fma_f32 v54, v18, v16, -1.0
	v_pk_mul_f32 v[16:17], v[56:57], v[56:57]
	v_readlane_b32 s9, v250, 55
	v_add_f32_e32 v16, v16, v17
	v_div_scale_f32 v17, s[0:1], v16, v16, 1.0
	v_rcp_f32_e32 v18, v17
	v_readlane_b32 s0, v255, 0
	v_readlane_b32 s1, v255, 1
	v_readlane_b32 s10, v250, 56
	v_fma_f32 v19, -v17, v18, 1.0
	v_fmac_f32_e32 v18, v19, v18
	v_div_scale_f32 v19, vcc, 1.0, v16, 1.0
	v_mul_f32_e32 v20, v19, v18
	v_fma_f32 v21, -v17, v20, v19
	v_fmac_f32_e32 v20, v21, v18
	v_fma_f32 v17, -v17, v20, v19
	v_div_fmas_f32 v17, v17, v18, v20
	v_div_fixup_f32 v58, v17, v16, 1.0
	v_lshl_add_u64 v[16:17], v[48:49], 4, s[0:1]
	v_lshlrev_b64 v[16:17], 2, v[16:17]
	v_readlane_b32 s11, v250, 57
	v_lshl_add_u64 v[20:21], s[8:9], 0, v[16:17]
	v_mov_b32_e32 v60, v57
	v_lshl_add_u64 v[44:45], s[10:11], 0, v[16:17]
	global_load_dwordx4 v[16:19], v[20:21], off offset:48
	global_load_dwordx4 v[24:27], v[20:21], off offset:32
	global_load_dwordx4 v[32:35], v[20:21], off offset:16
	global_load_dwordx4 v[40:43], v[20:21], off
	s_nop 0
	global_load_dwordx4 v[20:23], v[44:45], off offset:48
	global_load_dwordx4 v[28:31], v[44:45], off offset:32
	global_load_dwordx4 v[36:39], v[44:45], off offset:16
	s_nop 0
	global_load_dwordx4 v[44:47], v[44:45], off
	v_pk_mul_f32 v[60:61], v[60:61], v[54:55] op_sel:[0,1] op_sel_hi:[0,0]
	v_pk_fma_f32 v[62:63], v[56:57], v[54:55], v[60:61]
	v_pk_fma_f32 v[56:57], v[56:57], v[54:55], v[60:61] op_sel_hi:[0,1,1] neg_lo:[0,0,1] neg_hi:[0,0,1]
	v_mov_b32_e32 v63, v57
	v_pk_mul_f32 v[68:69], v[58:59], v[62:63] op_sel_hi:[0,1]
	v_readlane_b32 s0, v255, 2
	v_readlane_b32 s1, v255, 3
	v_mov_b32_e32 v53, v52
	v_readlane_b32 s5, v250, 51
	v_readlane_b32 s6, v250, 52
	v_readlane_b32 s7, v250, 53
	v_readlane_b32 s12, v250, 58
	v_readlane_b32 s13, v250, 59
	v_readlane_b32 s14, v250, 60
	v_readlane_b32 s15, v250, 61
	v_readlane_b32 s16, v250, 62
	v_readlane_b32 s17, v250, 63
	v_readlane_b32 s18, v251, 0
	v_readlane_b32 s19, v251, 1
	s_waitcnt vmcnt(4)
; template <bool FINAL>
; __device__ __forceinline__ void s5_wave(const Params& P, int j, int g, int idx0, int stride, char* ldsw) {
;     ...
;   {
;     const float4* br4 = reinterpret_cast<const float4*>(P.in[I_S5BRE] + ((size_t)jg * 64 + p) * 16);
;     const float4* bi4 = reinterpret_cast<const float4*>(P.in[I_S5BIM] + ((size_t)jg * 64 + p) * 16);
; #pragma unroll
;     for (int q = 0; q < 4; ++q) {
;       float4 a = br4[q], c = bi4[q];
;       bb[4 * q + 0] = (f32x2){cr * a.x - ci * c.x, cr * c.x + ci * a.x};
;       bb[4 * q + 1] = (f32x2){cr * a.y - ci * c.y, cr * c.y + ci * a.y};
;       bb[4 * q + 2] = (f32x2){cr * a.z - ci * c.z, cr * c.z + ci * a.z};
;       bb[4 * q + 3] = (f32x2){cr * a.w - ci * c.w, cr * c.w + ci * a.w};
;     }
;   }
	v_mov_b32_e32 v54, v43
	s_waitcnt vmcnt(0)
	v_pk_mul_f32 v[58:59], v[44:45], v[68:69] op_sel:[0,1] op_sel_hi:[0,0]
	v_pk_fma_f32 v[56:57], v[40:41], v[68:69], v[58:59] neg_lo:[0,0,1] neg_hi:[0,0,1]
	v_pk_fma_f32 v[58:59], v[40:41], v[68:69], v[58:59] op_sel_hi:[0,1,1]
	v_mov_b32_e32 v57, v59
	v_pk_mul_f32 v[58:59], v[44:45], v[68:69] op_sel:[1,1] op_sel_hi:[1,0]
	v_mov_b32_e32 v44, v41
	v_pk_fma_f32 v[44:45], v[44:45], v[68:69], v[58:59] neg_lo:[0,0,1] neg_hi:[0,0,1]
	v_pk_fma_f32 v[40:41], v[40:41], v[68:69], v[58:59] op_sel:[1,0,0]
	v_pk_mul_f32 v[58:59], v[46:47], v[68:69] op_sel:[0,1] op_sel_hi:[0,0]
	v_mov_b32_e32 v45, v41
	v_pk_fma_f32 v[40:41], v[42:43], v[68:69], v[58:59] neg_lo:[0,0,1] neg_hi:[0,0,1]
	v_pk_fma_f32 v[58:59], v[42:43], v[68:69], v[58:59] op_sel_hi:[0,1,1]
	v_mov_b32_e32 v42, v47
	v_pk_mul_f32 v[46:47], v[42:43], v[68:69] op_sel:[0,1] op_sel_hi:[0,0]
	v_mov_b32_e32 v42, v43
	v_mov_b32_e32 v41, v59
	v_pk_fma_f32 v[42:43], v[42:43], v[68:69], v[46:47] neg_lo:[0,0,1] neg_hi:[0,0,1]
	v_pk_fma_f32 v[46:47], v[54:55], v[68:69], v[46:47] op_sel_hi:[0,1,1]
	v_pk_mul_f32 v[58:59], v[36:37], v[68:69] op_sel:[0,1] op_sel_hi:[0,0]
	v_mov_b32_e32 v43, v47
	v_pk_fma_f32 v[46:47], v[32:33], v[68:69], v[58:59] neg_lo:[0,0,1] neg_hi:[0,0,1]
	v_pk_fma_f32 v[58:59], v[32:33], v[68:69], v[58:59] op_sel_hi:[0,1,1]
	v_mov_b32_e32 v47, v59
	v_pk_mul_f32 v[58:59], v[68:69], v[36:37] op_sel:[1,1] op_sel_hi:[0,1]
	v_mov_b32_e32 v36, v33
	v_pk_fma_f32 v[36:37], v[36:37], v[68:69], v[58:59] neg_lo:[0,0,1] neg_hi:[0,0,1]
	v_pk_fma_f32 v[32:33], v[32:33], v[68:69], v[58:59] op_sel:[1,0,0]
	v_pk_mul_f32 v[58:59], v[68:69], v[38:39] op_sel:[1,0] op_sel_hi:[0,0]
	v_mov_b32_e32 v37, v33
	v_pk_fma_f32 v[32:33], v[34:35], v[68:69], v[58:59] neg_lo:[0,0,1] neg_hi:[0,0,1]
	v_pk_fma_f32 v[58:59], v[34:35], v[68:69], v[58:59] op_sel_hi:[0,1,1]
	v_mov_b32_e32 v34, v39
	v_pk_mul_f32 v[38:39], v[68:69], v[34:35] op_sel:[1,0] op_sel_hi:[0,0]
	v_mov_b32_e32 v34, v35
	v_mov_b32_e32 v54, v35
	v_mov_b32_e32 v33, v59
	v_pk_fma_f32 v[34:35], v[34:35], v[68:69], v[38:39] neg_lo:[0,0,1] neg_hi:[0,0,1]
	v_pk_fma_f32 v[38:39], v[54:55], v[68:69], v[38:39] op_sel_hi:[0,1,1]
	v_pk_mul_f32 v[58:59], v[68:69], v[28:29] op_sel:[1,0] op_sel_hi:[0,0]
	v_mov_b32_e32 v35, v39
	v_pk_fma_f32 v[38:39], v[68:69], v[24:25], v[58:59] neg_lo:[0,0,1] neg_hi:[0,0,1]
	v_pk_fma_f32 v[58:59], v[68:69], v[24:25], v[58:59] op_sel_hi:[1,0,1]
	v_mov_b32_e32 v54, v27
	v_mov_b32_e32 v39, v59
	v_pk_mul_f32 v[58:59], v[68:69], v[28:29] op_sel:[1,1] op_sel_hi:[0,1]
	v_mov_b32_e32 v28, v25
	v_pk_fma_f32 v[28:29], v[68:69], v[28:29], v[58:59] neg_lo:[0,0,1] neg_hi:[0,0,1]
	v_pk_fma_f32 v[24:25], v[68:69], v[24:25], v[58:59] op_sel:[0,1,0]
	s_nop 0
	v_mov_b32_e32 v29, v25
	v_pk_mul_f32 v[24:25], v[68:69], v[30:31] op_sel:[1,0] op_sel_hi:[0,0]
	v_pk_fma_f32 v[58:59], v[68:69], v[26:27], v[24:25] neg_lo:[0,0,1] neg_hi:[0,0,1]
	v_pk_fma_f32 v[24:25], v[68:69], v[26:27], v[24:25] op_sel_hi:[1,0,1]
	v_mov_b32_e32 v26, v27
	v_mov_b32_e32 v24, v31
	v_mov_b32_e32 v59, v25
	v_pk_mul_f32 v[24:25], v[68:69], v[24:25] op_sel:[1,0] op_sel_hi:[0,0]
	v_pk_fma_f32 v[30:31], v[68:69], v[26:27], v[24:25] neg_lo:[0,0,1] neg_hi:[0,0,1]
	v_pk_fma_f32 v[24:25], v[68:69], v[54:55], v[24:25] op_sel_hi:[1,0,1]
	s_nop 0
	v_mov_b32_e32 v31, v25
	v_pk_mul_f32 v[24:25], v[68:69], v[20:21] op_sel:[1,0] op_sel_hi:[0,0]
	v_pk_fma_f32 v[60:61], v[68:69], v[16:17], v[24:25] neg_lo:[0,0,1] neg_hi:[0,0,1]
	v_pk_fma_f32 v[24:25], v[68:69], v[16:17], v[24:25] op_sel_hi:[1,0,1]
	v_pk_mul_f32 v[20:21], v[68:69], v[20:21] op_sel:[1,1] op_sel_hi:[0,1]
	v_mov_b32_e32 v24, v17
	v_pk_fma_f32 v[62:63], v[68:69], v[24:25], v[20:21] neg_lo:[0,0,1] neg_hi:[0,0,1]
	v_pk_fma_f32 v[16:17], v[68:69], v[16:17], v[20:21] op_sel:[0,1,0]
	v_mov_b32_e32 v20, v19
	v_mov_b32_e32 v63, v17
	v_pk_mul_f32 v[16:17], v[68:69], v[22:23] op_sel:[1,0] op_sel_hi:[0,0]
; template <bool FINAL>
; __device__ __forceinline__ void s5_wave(const Params& P, int j, int g, int idx0, int stride, char* ldsw) {
;     ...
;   float pr = lbr, pi = lbi;
; #pragma unroll
;   for (int s6 = 0; s6 < 6; ++s6) {
;     float nr2 = pr * pr - pi * pi, ni2 = 2.f * pr * pi;
;     pr = nr2; pi = ni2;
;   }
;   const int fr = lane & 15, fq = lane >> 4;
;   bf16x8 bc[4];
;   f32x4 dv4 = {0.f, 0.f, 0.f, 0.f};
;   if (FINAL) {
;     const float* crp = P.in[I_S5CRE] + ((size_t)jg * 16 + fr) * 64;
;     const float* cip = P.in[I_S5CIM] + ((size_t)jg * 16 + fr) * 64;
; #pragma unroll
;     for (int ks = 0; ks < 4; ++ks) {
;       float4 a = *reinterpret_cast<const float4*>(crp + ks * 16 + fq * 4);
;       float4 c = *reinterpret_cast<const float4*>(cip + ks * 16 + fq * 4);
;       union { bf16x8 v; uint32_t w[4]; } uu_;
;       uu_.w[0] = pack2(a.x, -c.x); uu_.w[1] = pack2(a.y, -c.y); uu_.w[2] = pack2(a.z, -c.z); uu_.w[3] = pack2(a.w, -c.w);
;       bc[ks] = uu_.v;
;     }
;     dv4 = *reinterpret_cast<const f32x4*>(P.in[I_S5D] + j * 512 + g * 16 + 4 * fq);
;   }
;   for (int idx = idx0; idx < 16384; idx += stride) {
	v_pk_fma_f32 v[64:65], v[68:69], v[18:19], v[16:17] neg_lo:[0,0,1] neg_hi:[0,0,1]
	v_pk_fma_f32 v[16:17], v[68:69], v[18:19], v[16:17] op_sel_hi:[1,0,1]
	v_mov_b32_e32 v18, v19
	v_mov_b32_e32 v16, v23
	v_mov_b32_e32 v65, v17
	v_pk_mul_f32 v[16:17], v[68:69], v[16:17] op_sel:[1,0] op_sel_hi:[0,0]
	v_pk_fma_f32 v[66:67], v[68:69], v[18:19], v[16:17] neg_lo:[0,0,1] neg_hi:[0,0,1]
	v_pk_fma_f32 v[16:17], v[68:69], v[20:21], v[16:17] op_sel_hi:[1,0,1]
	v_mov_b32_e32 v61, v25
	v_mul_f32_e32 v16, v55, v55
	v_fma_f32 v16, v52, v52, -v16
	v_mov_b32_e32 v67, v17
	v_add_f32_e32 v17, v52, v52
	v_mov_b32_e32 v54, v16
	v_pk_mul_f32 v[18:19], v[16:17], v[54:55]
	v_mov_b32_e32 v54, v55
	v_pk_mov_b32 v[16:17], v[18:19], v[16:17] op_sel:[1,0]
	v_mov_b32_e32 v182, v19
	v_pk_mul_f32 v[20:21], v[16:17], v[182:183]
	v_pk_fma_f32 v[16:17], v[16:17], v[182:183], v[18:19] neg_lo:[1,0,0] neg_hi:[1,0,0]
	v_pk_mul_f32 v[22:23], v[18:19], v[20:21]
	v_pk_mov_b32 v[18:19], v[18:19], v[16:17] op_sel:[1,0]
	v_mov_b32_e32 v182, v21
	v_pk_mul_f32 v[18:19], v[18:19], v[182:183]
	v_mov_b32_e32 v24, v16
	v_mov_b32_e32 v25, v23
	v_mov_b32_e32 v17, v19
	v_pk_mul_f32 v[16:17], v[24:25], v[16:17]
	v_pk_mul_f32 v[20:21], v[22:23], v[18:19]
	v_pk_fma_f32 v[18:19], v[22:23], v[18:19], v[16:17] op_sel:[1,0,0] neg_lo:[1,0,0] neg_hi:[1,0,0]
	v_pk_mul_f32 v[20:21], v[16:17], v[20:21]
	v_mov_b32_e32 v182, v18
	v_pk_mul_f32 v[22:23], v[18:19], v[182:183] op_sel_hi:[0,1]
	v_mov_b32_e32 v16, v21
	v_pk_fma_f32 v[18:19], v[18:19], v[182:183], v[16:17] op_sel_hi:[0,1,1] neg_lo:[0,0,1] neg_hi:[0,0,1]
	v_pk_mul_f32 v[16:17], v[22:23], v[16:17]
	v_mul_f32_e32 v20, v18, v18
	v_mov_b32_e32 v19, v17
	v_add_f32_e32 v16, v18, v18
	v_pk_fma_f32 v[18:19], v[18:19], v[18:19], v[20:21] op_sel_hi:[1,1,0] neg_lo:[1,0,0] neg_hi:[1,0,0]
	v_mov_b32_e32 v20, v17
	v_mov_b32_e32 v21, v19
	v_mov_b32_e32 v17, v19
	v_pk_mul_f32 v[16:17], v[20:21], v[16:17]
	v_mov_b32_e32 v20, v183
	v_pk_mov_b32 v[18:19], v[18:19], v[16:17] op_sel:[1,0]
	v_mov_b32_e32 v21, v16
	v_pk_mul_f32 v[22:23], v[18:19], v[20:21]
	v_pk_fma_f32 v[20:21], v[18:19], v[20:21], v[16:17] neg_lo:[1,0,0] neg_hi:[1,0,0]
	v_pk_mul_f32 v[22:23], v[16:17], v[22:23]
	v_lshl_add_u64 v[16:17], v[50:51], 2, s[0:1]
	global_load_dwordx4 v[16:19], v[16:17], off
	v_readlane_b32 s0, v251, 60
	v_mov_b32_e32 v69, v21
	v_mov_b32_e32 v72, v21
	v_lshl_add_u32 v24, v50, 2, s0
	v_lshl_add_u32 v91, v48, 2, s0
	v_readlane_b32 s0, v252, 11
	v_readlane_b32 s1, v252, 12
	v_mov_b32_e32 v73, v21
	v_pk_mov_b32 v[76:77], v[20:21], v[22:23] op_sel:[1,0]
	v_lshl_add_u64 v[70:71], v[50:51], 1, s[0:1]
	v_readlane_b32 s0, v253, 52
	v_lshlrev_b64 v[20:21], 3, v[48:49]
	v_readlane_b32 s1, v253, 53
	v_mul_u32_u24_e32 v25, 0x110, v90
	v_mov_b32_e32 v68, v22
	v_lshl_add_u64 v[78:79], s[0:1], 0, v[20:21]
	v_readlane_b32 s0, v253, 54
	v_readlane_b32 s1, v253, 55
	v_mov_b32_e32 v74, v22
	v_mov_b32_e32 v75, v22
	v_lshl_add_u64 v[80:81], s[0:1], 0, v[20:21]
	v_readlane_b32 s0, v251, 22
	v_add_u32_e32 v92, v24, v25
	s_mov_b32 s2, s0
	v_readlane_b32 s1, v251, 23
	v_and_b32_e32 v109, 31, v48
	v_mul_u32_u24_e32 v110, 0xa00, v109
	v_mov_b32_e32 v111, 0
	v_cmp_gt_u32_e32 vcc, 32, v48
	s_nop 1
	v_cndmask_b32_e64 v108, 0, 16, vcc
	v_permlane32_swap_b32_e32 v56, v44
	v_permlane32_swap_b32_e32 v57, v45
	v_permlane32_swap_b32_e32 v40, v42
	v_permlane32_swap_b32_e32 v41, v43
	v_permlane32_swap_b32_e32 v46, v36
	v_permlane32_swap_b32_e32 v47, v37
	v_permlane32_swap_b32_e32 v32, v34
	v_permlane32_swap_b32_e32 v33, v35
	v_permlane32_swap_b32_e32 v38, v28
	v_permlane32_swap_b32_e32 v39, v29
	v_permlane32_swap_b32_e32 v58, v30
	v_permlane32_swap_b32_e32 v59, v31
	v_permlane32_swap_b32_e32 v60, v62
	v_permlane32_swap_b32_e32 v61, v63
	v_permlane32_swap_b32_e32 v64, v66
	v_permlane32_swap_b32_e32 v65, v67
	s_bitcmp1_b32 s2, 2
	s_cbranch_scc0 .LBB0_430
	s_sleep 40

; template <bool FINAL>
; __device__ __forceinline__ void s5_wave(const Params& P, int j, int g, int idx0, int stride, char* ldsw) {
;     ...
;   const int jg = j * 32 + g;
;   const float lr = P.in[I_S5LRE][jg * 64 + p], li = P.in[I_S5LIM][jg * 64 + p];
;   const float dt = expf(P.in[I_S5LOGDT][jg]);
;   const float er = expf(lr * dt);
;   float sn, cs;
;   sincosf(li * dt, &sn, &cs);
;   const float lbr = er * cs, lbi = er * sn;
;   const float nr = lbr - 1.f, ni = lbi;
;   const float den = 1.f / (lr * lr + li * li);
;   const float cr = (nr * lr + ni * li) * den, ci = (ni * lr - nr * li) * den;
.LBB0_520:
	s_waitcnt vmcnt(0)
	v_mul_f32_e32 v2, v36, v2
	v_mul_f32_e32 v5, 0x3fb8aa3b, v2
	s_mov_b32 s0, 0x3fb8aa3b
	v_fma_f32 v6, v2, s0, -v5
	v_rndne_f32_e32 v7, v5
	v_fmac_f32_e32 v6, 0x32a5705f, v2
	v_sub_f32_e32 v5, v5, v7
	v_add_f32_e32 v5, v5, v6
	v_exp_f32_e32 v5, v5
	v_cvt_i32_f32_e32 v6, v7
	s_mov_b32 s0, 0xc2ce8ed0
	v_cmp_ngt_f32_e32 vcc, s0, v2
	s_mov_b32 s0, 0x42b17218
	v_ldexp_f32 v5, v5, v6
	v_cndmask_b32_e32 v5, 0, v5, vcc
	v_cmp_nlt_f32_e32 vcc, s0, v2
	v_xor_b32_e32 v1, v1, v0
	s_movk_i32 s0, 0x1f8
	v_cndmask_b32_e32 v2, v226, v5, vcc
	v_mul_f32_e32 v5, v3, v3
	v_fmamk_f32 v6, v5, 0xb94c1982, v219
	v_fmaak_f32 v6, v5, v6, 0xbe2aaa9d
	v_mul_f32_e32 v6, v5, v6
	v_fmac_f32_e32 v3, v3, v6
	v_fmamk_f32 v6, v5, 0x37d75334, v220
	v_fmaak_f32 v6, v5, v6, 0x3d2aabf7
	v_fmaak_f32 v6, v5, v6, 0xbf000004
	v_fma_f32 v5, v5, v6, 1.0
	v_lshlrev_b32_e32 v6, 30, v4
	v_and_b32_e32 v4, 1, v4
	v_cmp_eq_u32_e32 vcc, 0, v4
	v_and_b32_e32 v6, 0x80000000, v6
	v_ashrrev_i32_e32 v33, 31, v32
	v_cndmask_b32_e32 v4, v5, v3, vcc
	v_xor_b32_e32 v3, 0x80000000, v3
	v_xor_b32_e32 v1, v1, v4
	v_cndmask_b32_e32 v3, v3, v5, vcc
	v_cmp_class_f32_e64 vcc, v0, s0
	v_xor_b32_e32 v0, v1, v6
	v_xor_b32_e32 v3, v3, v6
	v_cndmask_b32_e32 v1, v229, v0, vcc
	v_cndmask_b32_e32 v0, v229, v3, vcc
	v_pk_mul_f32 v[34:35], v[2:3], v[0:1] op_sel_hi:[0,1]
	v_pk_mul_f32 v[0:1], v[36:37], v[36:37]
	v_readlane_b32 s4, v250, 50
	v_add_f32_e32 v0, v0, v1
	v_div_scale_f32 v1, s[0:1], v0, v0, 1.0
	v_rcp_f32_e32 v2, v1
	v_readlane_b32 s0, v255, 0
	v_readlane_b32 s1, v255, 1
	v_readlane_b32 s8, v250, 54
	v_fma_f32 v3, -v1, v2, 1.0
	v_fmac_f32_e32 v2, v3, v2
	v_div_scale_f32 v3, vcc, 1.0, v0, 1.0
	v_mul_f32_e32 v4, v3, v2
	v_fma_f32 v5, -v1, v4, v3
	v_fmac_f32_e32 v4, v5, v2
	v_fma_f32 v1, -v1, v4, v3
	v_div_fmas_f32 v1, v1, v2, v4
	v_div_fixup_f32 v40, v1, v0, 1.0
	v_lshl_add_u64 v[0:1], v[32:33], 4, s[0:1]
	v_lshlrev_b64 v[0:1], 2, v[0:1]
	v_readlane_b32 s9, v250, 55
	v_readlane_b32 s10, v250, 56
	v_readlane_b32 s11, v250, 57
	v_lshl_add_u64 v[4:5], s[8:9], 0, v[0:1]
	v_add_f32_e32 v38, -1.0, v34
	v_lshl_add_u64 v[28:29], s[10:11], 0, v[0:1]
	global_load_dwordx4 v[0:3], v[4:5], off offset:48
	global_load_dwordx4 v[8:11], v[4:5], off offset:32
	global_load_dwordx4 v[16:19], v[4:5], off offset:16
	global_load_dwordx4 v[24:27], v[4:5], off
	s_nop 0
	global_load_dwordx4 v[4:7], v[28:29], off offset:48
	global_load_dwordx4 v[12:15], v[28:29], off offset:32
	global_load_dwordx4 v[20:23], v[28:29], off offset:16
	s_nop 0
	global_load_dwordx4 v[28:31], v[28:29], off
	v_mov_b32_e32 v42, v37
	v_mov_b32_e32 v44, v35
	v_mov_b32_e32 v45, v38
	v_mov_b32_e32 v39, v35
	v_pk_mul_f32 v[42:43], v[42:43], v[44:45] op_sel_hi:[0,1]
	v_pk_fma_f32 v[44:45], v[36:37], v[38:39], v[42:43]
	v_pk_fma_f32 v[36:37], v[36:37], v[38:39], v[42:43] op_sel_hi:[0,1,1] neg_lo:[0,0,1] neg_hi:[0,0,1]
	v_mov_b32_e32 v45, v37
	v_pk_mul_f32 v[44:45], v[40:41], v[44:45] op_sel_hi:[0,1]
	v_readlane_b32 s0, v252, 6
	v_readlane_b32 s1, v252, 7
	v_pk_mov_b32 v[46:47], v[34:35], v[34:35] op_sel:[1,0]
	v_readlane_b32 s5, v250, 51
	v_readlane_b32 s6, v250, 52
	v_readlane_b32 s7, v250, 53
	v_readlane_b32 s12, v250, 58
	v_readlane_b32 s13, v250, 59
	v_readlane_b32 s14, v250, 60
	v_readlane_b32 s15, v250, 61
	v_readlane_b32 s16, v250, 62
	v_readlane_b32 s17, v250, 63
	v_readlane_b32 s18, v251, 0
	v_readlane_b32 s19, v251, 1
	s_waitcnt vmcnt(0)
; template <bool FINAL>
; __device__ __forceinline__ void s5_wave(const Params& P, int j, int g, int idx0, int stride, char* ldsw) {
;     ...
;   {
;     const float4* br4 = reinterpret_cast<const float4*>(P.in[I_S5BRE] + ((size_t)jg * 64 + p) * 16);
;     const float4* bi4 = reinterpret_cast<const float4*>(P.in[I_S5BIM] + ((size_t)jg * 64 + p) * 16);
; #pragma unroll
;     for (int q = 0; q < 4; ++q) {
;       float4 a = br4[q], c = bi4[q];
;       bb[4 * q + 0] = (f32x2){cr * a.x - ci * c.x, cr * c.x + ci * a.x};
;       bb[4 * q + 1] = (f32x2){cr * a.y - ci * c.y, cr * c.y + ci * a.y};
;       bb[4 * q + 2] = (f32x2){cr * a.z - ci * c.z, cr * c.z + ci * a.z};
;       bb[4 * q + 3] = (f32x2){cr * a.w - ci * c.w, cr * c.w + ci * a.w};
;     }
;   }
;   const u16* Zo = reinterpret_cast<const u16*>(P.ws + OFF_BIG);
;   float2* hend = reinterpret_cast<float2*>(P.ws + OFF_S5END);
;   uint32_t* hbuf = reinterpret_cast<uint32_t*>(ldsw);
;   float pr = lbr, pi = lbi;
; #pragma unroll
;   for (int s6 = 0; s6 < 6; ++s6) {
;     float nr2 = pr * pr - pi * pi, ni2 = 2.f * pr * pi;
;     pr = nr2; pi = ni2;
;   }
;   const int fr = lane & 15, fq = lane >> 4;
;   bf16x8 bc[4];
;   f32x4 dv4 = {0.f, 0.f, 0.f, 0.f};
;   if (FINAL) {
;     const float* crp = P.in[I_S5CRE] + ((size_t)jg * 16 + fr) * 64;
;     const float* cip = P.in[I_S5CIM] + ((size_t)jg * 16 + fr) * 64;
; #pragma unroll
;     for (int ks = 0; ks < 4; ++ks) {
;       float4 a = *reinterpret_cast<const float4*>(crp + ks * 16 + fq * 4);
;       float4 c = *reinterpret_cast<const float4*>(cip + ks * 16 + fq * 4);
;       union { bf16x8 v; uint32_t w[4]; } uu_;
;       uu_.w[0] = pack2(a.x, -c.x); uu_.w[1] = pack2(a.y, -c.y); uu_.w[2] = pack2(a.z, -c.z); uu_.w[3] = pack2(a.w, -c.w);
;       bc[ks] = uu_.v;
;     }
;     dv4 = *reinterpret_cast<const f32x4*>(P.in[I_S5D] + j * 512 + g * 16 + 4 * fq);
;   }
;   for (int idx = idx0; idx < 16384; idx += stride) {
;   const int b = idx >> 11, chunk = ((idx >> 5) + 8 * b) & 63;
;   const size_t rowbase = (size_t)b * 4096 + chunk * 64;
;   const u16* up = Zo + (rowbase + lane) * 1280 + 768 + g * 16;
;   const uint4 u0 = *reinterpret_cast<const uint4*>(up);
;   const uint4 u1 = *reinterpret_cast<const uint4*>(up + 8);
	v_pk_mul_f32 v[38:39], v[28:29], v[44:45] op_sel:[0,1] op_sel_hi:[0,0]
	v_pk_fma_f32 v[36:37], v[24:25], v[44:45], v[38:39] neg_lo:[0,0,1] neg_hi:[0,0,1]
	v_pk_fma_f32 v[38:39], v[24:25], v[44:45], v[38:39] op_sel_hi:[0,1,1]
	v_mov_b32_e32 v37, v39
	v_pk_mul_f32 v[38:39], v[28:29], v[44:45] op_sel:[1,1] op_sel_hi:[1,0]
	v_mov_b32_e32 v28, v25
	v_pk_fma_f32 v[28:29], v[28:29], v[44:45], v[38:39] neg_lo:[0,0,1] neg_hi:[0,0,1]
	v_pk_fma_f32 v[24:25], v[24:25], v[44:45], v[38:39] op_sel:[1,0,0]
	v_pk_mul_f32 v[38:39], v[30:31], v[44:45] op_sel:[0,1] op_sel_hi:[0,0]
	v_mov_b32_e32 v29, v25
	v_pk_fma_f32 v[24:25], v[26:27], v[44:45], v[38:39] neg_lo:[0,0,1] neg_hi:[0,0,1]
	v_pk_fma_f32 v[38:39], v[26:27], v[44:45], v[38:39] op_sel_hi:[0,1,1]
	v_mov_b32_e32 v26, v31
	v_pk_mul_f32 v[30:31], v[26:27], v[44:45] op_sel:[0,1] op_sel_hi:[0,0]
	v_mov_b32_e32 v26, v27
	v_mov_b32_e32 v38, v27
	v_mov_b32_e32 v25, v39
	v_pk_fma_f32 v[26:27], v[26:27], v[44:45], v[30:31] neg_lo:[0,0,1] neg_hi:[0,0,1]
	v_pk_fma_f32 v[30:31], v[38:39], v[44:45], v[30:31] op_sel_hi:[0,1,1]
	v_pk_mul_f32 v[38:39], v[20:21], v[44:45] op_sel:[0,1] op_sel_hi:[0,0]
	v_mov_b32_e32 v27, v31
	v_pk_fma_f32 v[30:31], v[16:17], v[44:45], v[38:39] neg_lo:[0,0,1] neg_hi:[0,0,1]
	v_pk_fma_f32 v[38:39], v[16:17], v[44:45], v[38:39] op_sel_hi:[0,1,1]
	v_mov_b32_e32 v31, v39
	v_pk_mul_f32 v[38:39], v[44:45], v[20:21] op_sel:[1,1] op_sel_hi:[0,1]
	v_mov_b32_e32 v20, v17
	v_pk_fma_f32 v[20:21], v[20:21], v[44:45], v[38:39] neg_lo:[0,0,1] neg_hi:[0,0,1]
	v_pk_fma_f32 v[16:17], v[16:17], v[44:45], v[38:39] op_sel:[1,0,0]
	v_pk_mul_f32 v[38:39], v[44:45], v[22:23] op_sel:[1,0] op_sel_hi:[0,0]
	v_mov_b32_e32 v21, v17
	v_pk_fma_f32 v[16:17], v[18:19], v[44:45], v[38:39] neg_lo:[0,0,1] neg_hi:[0,0,1]
	v_pk_fma_f32 v[38:39], v[18:19], v[44:45], v[38:39] op_sel_hi:[0,1,1]
	v_mov_b32_e32 v18, v23
	v_pk_mul_f32 v[22:23], v[44:45], v[18:19] op_sel:[1,0] op_sel_hi:[0,0]
	v_mov_b32_e32 v18, v19
	v_mov_b32_e32 v38, v19
	v_mov_b32_e32 v17, v39
	v_pk_fma_f32 v[18:19], v[18:19], v[44:45], v[22:23] neg_lo:[0,0,1] neg_hi:[0,0,1]
	v_pk_fma_f32 v[22:23], v[38:39], v[44:45], v[22:23] op_sel_hi:[0,1,1]
	v_pk_mul_f32 v[38:39], v[44:45], v[12:13] op_sel:[1,0] op_sel_hi:[0,0]
	v_mov_b32_e32 v19, v23
	v_pk_fma_f32 v[22:23], v[44:45], v[8:9], v[38:39] neg_lo:[0,0,1] neg_hi:[0,0,1]
	v_pk_fma_f32 v[38:39], v[44:45], v[8:9], v[38:39] op_sel_hi:[1,0,1]
	s_nop 0
	v_mov_b32_e32 v23, v39
	v_pk_mul_f32 v[38:39], v[44:45], v[12:13] op_sel:[1,1] op_sel_hi:[0,1]
	v_mov_b32_e32 v12, v9
	v_pk_fma_f32 v[12:13], v[44:45], v[12:13], v[38:39] neg_lo:[0,0,1] neg_hi:[0,0,1]
	v_pk_fma_f32 v[8:9], v[44:45], v[8:9], v[38:39] op_sel:[0,1,0]
	v_pk_mul_f32 v[38:39], v[44:45], v[14:15] op_sel:[1,0] op_sel_hi:[0,0]
	v_mov_b32_e32 v13, v9
	v_pk_fma_f32 v[8:9], v[44:45], v[10:11], v[38:39] neg_lo:[0,0,1] neg_hi:[0,0,1]
	v_pk_fma_f32 v[38:39], v[44:45], v[10:11], v[38:39] op_sel_hi:[1,0,1]
	v_mov_b32_e32 v10, v15
	v_pk_mul_f32 v[14:15], v[44:45], v[10:11] op_sel:[1,0] op_sel_hi:[0,0]
	v_mov_b32_e32 v10, v11
	v_mov_b32_e32 v38, v11
	v_mov_b32_e32 v9, v39
	v_pk_fma_f32 v[10:11], v[44:45], v[10:11], v[14:15] neg_lo:[0,0,1] neg_hi:[0,0,1]
	v_pk_fma_f32 v[14:15], v[44:45], v[38:39], v[14:15] op_sel_hi:[1,0,1]
	v_pk_mul_f32 v[38:39], v[44:45], v[4:5] op_sel:[1,0] op_sel_hi:[0,0]
	v_mov_b32_e32 v11, v15
	v_pk_fma_f32 v[14:15], v[44:45], v[0:1], v[38:39] neg_lo:[0,0,1] neg_hi:[0,0,1]
	v_pk_fma_f32 v[38:39], v[44:45], v[0:1], v[38:39] op_sel_hi:[1,0,1]
	v_pk_mul_f32 v[4:5], v[44:45], v[4:5] op_sel:[1,1] op_sel_hi:[0,1]
	v_mov_b32_e32 v38, v1
	v_mov_b32_e32 v15, v39
	v_pk_fma_f32 v[38:39], v[44:45], v[38:39], v[4:5] neg_lo:[0,0,1] neg_hi:[0,0,1]
	v_pk_fma_f32 v[0:1], v[44:45], v[0:1], v[4:5] op_sel:[0,1,0]
	v_mov_b32_e32 v4, v3
	v_mov_b32_e32 v39, v1
	v_pk_mul_f32 v[0:1], v[44:45], v[6:7] op_sel:[1,0] op_sel_hi:[0,0]
	v_pk_fma_f32 v[40:41], v[44:45], v[2:3], v[0:1] neg_lo:[0,0,1] neg_hi:[0,0,1]
	v_pk_fma_f32 v[0:1], v[44:45], v[2:3], v[0:1] op_sel_hi:[1,0,1]
	v_mov_b32_e32 v2, v3
	v_mov_b32_e32 v0, v7
	v_mov_b32_e32 v41, v1
	v_pk_mul_f32 v[0:1], v[44:45], v[0:1] op_sel:[1,0] op_sel_hi:[0,0]
	v_pk_fma_f32 v[42:43], v[44:45], v[2:3], v[0:1] neg_lo:[0,0,1] neg_hi:[0,0,1]
	v_pk_fma_f32 v[0:1], v[44:45], v[4:5], v[0:1] op_sel_hi:[1,0,1]
	v_lshl_add_u64 v[44:45], v[32:33], 3, s[0:1]
	v_readlane_b32 s0, v251, 22
	v_mov_b32_e32 v43, v1
	s_mov_b32 s2, s0
	v_readlane_b32 s1, v251, 23
	v_and_b32_e32 v109, 31, v32
	v_mul_u32_u24_e32 v110, 0xa00, v109
	v_mov_b32_e32 v111, 0
	v_cmp_gt_u32_e32 vcc, 32, v32
	s_nop 1
	v_cndmask_b32_e64 v108, 0, 16, vcc
	v_permlane32_swap_b32_e32 v36, v28
	v_permlane32_swap_b32_e32 v37, v29
	v_permlane32_swap_b32_e32 v24, v26
	v_permlane32_swap_b32_e32 v25, v27
	v_permlane32_swap_b32_e32 v30, v20
	v_permlane32_swap_b32_e32 v31, v21
	v_permlane32_swap_b32_e32 v16, v18
	v_permlane32_swap_b32_e32 v17, v19
	v_permlane32_swap_b32_e32 v22, v12
	v_permlane32_swap_b32_e32 v23, v13
	v_permlane32_swap_b32_e32 v8, v10
	v_permlane32_swap_b32_e32 v9, v11
	v_permlane32_swap_b32_e32 v14, v38
	v_permlane32_swap_b32_e32 v15, v39
	v_permlane32_swap_b32_e32 v40, v42
	v_permlane32_swap_b32_e32 v41, v43
	v_readlane_b32 s1, v252, 1
	s_lshl_b32 s1, s1, 1
	s_add_u32 s5, s1, 0x17840600
	s_ashr_i32 s0, s2, 11
	s_lshr_b32 s1, s2, 5
	s_lshl_b32 s4, s0, 3
	s_add_i32 s4, s4, s1
	s_and_b32 s4, s4, 63
	s_lshl_b32 s6, s0, 12
	s_lshl_b32 s7, s4, 6
	s_or_b32 s6, s6, s7
	s_mul_i32 s6, s6, 0xa00
	s_add_u32 s6, s6, s5
	s_add_u32 s8, s90, s6
	s_addc_u32 s9, s91, 0
	v_lshl_add_u64 v[64:65], v[110:111], 0, s[8:9]
	global_load_dwordx4 v[0:3], v[64:65], off
	global_load_dwordx4 v[4:7], v[64:65], off offset:16
	global_load_dword v68, v[64:65], off
	s_bitcmp1_b32 s2, 2
	s_cbranch_scc0 .Ls5p1_job
	s_sleep 40
